# P1 loop-header vmcnt(0) hoisted; c_phase Q wait hoisted out of step loop; c_phase epilogue wsf reads batched
# speedup vs baseline: 1.0150x; 1.0150x over previous
; #define PG8_STAGE(bufoff, gbase, voff) do { _Pragma("unroll") for (int _i = 0; _i < 2; ++_i) \
;         __builtin_amdgcn_global_load_lds((const unsigned*)((const char*)(gbase) + (voff)[_i]), (PG8_LAS unsigned*)(lds + (bufoff) + ldsw + _i * 8192), 16, 0, 0); } while (0)
; #define PG8_LDA(dst, b, h) do { _Pragma("unroll") for (int m = 0; m < 4; ++m) _Pragma("unroll") for (int k = 0; k < 2; ++k) dst[m][k] = *(const PG8_LAS bf16x8*)(lds + PG8_SA(b, h) + aoff + m * 2048 + k * 1024); } while (0)
; #define PG8_LDB(dst, b, h) do { _Pragma("unroll") for (int n = 0; n < 2; ++n) _Pragma("unroll") for (int k = 0; k < 2; ++k) dst[n][k] = *(const PG8_LAS bf16x8*)(lds + PG8_SB(b, h) + boff + n * 2048 + k * 1024); } while (0)
; #define PG8_WAIT_V(n) asm volatile("s_waitcnt vmcnt(" #n ")" ::: "memory")
; #define PG8_WAIT_L(n) asm volatile("s_waitcnt lgkmcnt(" #n ")" ::: "memory")
; #define PG8_BAR __builtin_amdgcn_s_barrier()
; #define PG8_SCHED __builtin_amdgcn_sched_barrier(0)
; template <class Epi, class Sched, bool ALIGN_EPI = false, bool SP2 = false>
; __device__ __forceinline__ void gemm_phase(PG8_LAS unsigned char* lds, const Gemm g, const Sched& S, const Epi& E, int wave0) {
;     ...
;         const bool has_next = S.next(ui + 1, nxt);
;         const char* nA = has_next ? a_base(g, nxt) : cA; const char* nB = has_next ? (const char*)g.Bt + (size_t)nxt.pn * tstep : cB;
;         for (int t = 0; t < nt; t += 2) {
;             const bool last = (t == nt - 2);
;             const char* a1 = cA + (size_t)(t + 1) * kstepA;
;             const char* a2 = last ? nA : cA + (size_t)(t + 2) * kstepA; const char* b2 = last ? nB : cB + (size_t)(t + 2) * kstep;
;             const char* a3 = a2 + kstepA; const char* b3 = b2 + kstep;
;             if (last && has_next) S.a_ready(nxt);
;             if constexpr (SP2) {
;             PG8_LDB(B0, 0, 0); PG8_LDB(B1, 0, 1); PG8_SCHED; PG8_LDA(At, 0, 0); PG8_STAGE(PG8_SA(1, 1), a1 + hstepA, voffA);
;             PG8_WAIT_V(8); PG8_WAIT_L(0); PG8_BAR; PG8_MMA(0, 0, At, B0); PG8_MMA(0, 1, At, B1); PG8_BAR; PG8_SCHED;
;     ...
;         for (int a = 0; a < 2; ++a)
; #pragma unroll
;             for (int b = 0; b < 2; ++b)
; #pragma unroll
;                 for (int m = 0; m < 4; ++m)
; #pragma unroll
;                     for (int n = 0; n < 2; ++n) acc[a][b][m][n] = (f32x4){0.f, 0.f, 0.f, 0.f};
;         cur = nxt; cA = nA; cB = nB; ++ui;
.LBB0_220:
	s_ashr_i32 s25, s24, 31
	s_lshl_b64 s[6:7], s[24:25], 19
	s_add_u32 s26, s38, s6
	s_addc_u32 s27, s39, s7
	s_and_b64 s[6:7], s[8:9], exec
	s_cselect_b32 s5, s27, s31
	s_cselect_b32 s25, s26, s30
	s_ashr_i32 s23, s22, 31
	s_lshl_b64 s[6:7], s[22:23], 19
	s_add_u32 s28, s2, s6
	s_addc_u32 s29, s3, s7
	s_and_b64 s[6:7], s[8:9], exec
	s_cselect_b32 s23, s29, s11
	s_cselect_b32 s34, s28, s10
	s_add_u32 s35, s10, 0x100
	s_addc_u32 s36, s11, 0
	s_add_u32 s6, s30, 0x40080
	v_mov_b32_e32 v0, 0
	s_addc_u32 s7, s31, 0
	s_mov_b32 s37, -2
	v_mov_b32_e32 v1, v0
	v_mov_b32_e32 v2, v0
	v_mov_b32_e32 v3, v0
	v_mov_b32_e32 v4, v0
	v_mov_b32_e32 v5, v0
	v_mov_b32_e32 v6, v0
	v_mov_b32_e32 v7, v0
	v_mov_b32_e32 v16, v0
	v_mov_b32_e32 v17, v0
	v_mov_b32_e32 v18, v0
	v_mov_b32_e32 v19, v0
	v_mov_b32_e32 v20, v0
	v_mov_b32_e32 v21, v0
	v_mov_b32_e32 v22, v0
	v_mov_b32_e32 v23, v0
	v_mov_b32_e32 v32, v0
	v_mov_b32_e32 v33, v0
	v_mov_b32_e32 v34, v0
	v_mov_b32_e32 v35, v0
	v_mov_b32_e32 v36, v0
	v_mov_b32_e32 v37, v0
	v_mov_b32_e32 v38, v0
	v_mov_b32_e32 v39, v0
	v_mov_b32_e32 v56, v0
	v_mov_b32_e32 v57, v0
	v_mov_b32_e32 v58, v0
	v_mov_b32_e32 v59, v0
	v_mov_b32_e32 v60, v0
	v_mov_b32_e32 v61, v0
	v_mov_b32_e32 v62, v0
	v_mov_b32_e32 v63, v0
	v_mov_b32_e32 v8, v0
	v_mov_b32_e32 v9, v0
	v_mov_b32_e32 v10, v0
	v_mov_b32_e32 v11, v0
	v_mov_b32_e32 v12, v0
	v_mov_b32_e32 v13, v0
	v_mov_b32_e32 v14, v0
	v_mov_b32_e32 v15, v0
	v_mov_b32_e32 v24, v0
	v_mov_b32_e32 v25, v0
	v_mov_b32_e32 v26, v0
	v_mov_b32_e32 v27, v0
	v_mov_b32_e32 v28, v0
	v_mov_b32_e32 v29, v0
	v_mov_b32_e32 v30, v0
	v_mov_b32_e32 v31, v0
	v_mov_b32_e32 v40, v0
	v_mov_b32_e32 v41, v0
	v_mov_b32_e32 v42, v0
	v_mov_b32_e32 v43, v0
	v_mov_b32_e32 v44, v0
	v_mov_b32_e32 v45, v0
	v_mov_b32_e32 v46, v0
	v_mov_b32_e32 v47, v0
	v_mov_b32_e32 v64, v0
	v_mov_b32_e32 v65, v0
	v_mov_b32_e32 v66, v0
	v_mov_b32_e32 v67, v0
	v_mov_b32_e32 v68, v0
	v_mov_b32_e32 v69, v0
	v_mov_b32_e32 v70, v0
	v_mov_b32_e32 v71, v0
	v_mov_b32_e32 v80, v0
	v_mov_b32_e32 v81, v0
	v_mov_b32_e32 v82, v0
	v_mov_b32_e32 v83, v0
	v_mov_b32_e32 v84, v0
	v_mov_b32_e32 v85, v0
	v_mov_b32_e32 v86, v0
	v_mov_b32_e32 v87, v0
	v_mov_b32_e32 v104, v0
	v_mov_b32_e32 v105, v0
	v_mov_b32_e32 v106, v0
	v_mov_b32_e32 v107, v0
	v_mov_b32_e32 v108, v0
	v_mov_b32_e32 v109, v0
	v_mov_b32_e32 v110, v0
	v_mov_b32_e32 v111, v0
	v_mov_b32_e32 v128, v0
	v_mov_b32_e32 v129, v0
	v_mov_b32_e32 v130, v0
	v_mov_b32_e32 v131, v0
	v_mov_b32_e32 v132, v0
	v_mov_b32_e32 v133, v0
	v_mov_b32_e32 v134, v0
	v_mov_b32_e32 v135, v0
	v_mov_b32_e32 v144, v0
	v_mov_b32_e32 v145, v0
	v_mov_b32_e32 v146, v0
	v_mov_b32_e32 v147, v0
	v_mov_b32_e32 v148, v0
	v_mov_b32_e32 v149, v0
	v_mov_b32_e32 v150, v0
	v_mov_b32_e32 v151, v0
	v_mov_b32_e32 v96, v0
	v_mov_b32_e32 v97, v0
	v_mov_b32_e32 v98, v0
	v_mov_b32_e32 v99, v0
	v_mov_b32_e32 v100, v0
	v_mov_b32_e32 v101, v0
	v_mov_b32_e32 v102, v0
	v_mov_b32_e32 v103, v0
	v_mov_b32_e32 v120, v0
	v_mov_b32_e32 v121, v0
	v_mov_b32_e32 v122, v0
	v_mov_b32_e32 v123, v0
	v_mov_b32_e32 v124, v0
	v_mov_b32_e32 v125, v0
	v_mov_b32_e32 v126, v0
	v_mov_b32_e32 v127, v0
	v_mov_b32_e32 v136, v0
	v_mov_b32_e32 v137, v0
	v_mov_b32_e32 v138, v0
	v_mov_b32_e32 v139, v0
	v_mov_b32_e32 v140, v0
	v_mov_b32_e32 v141, v0
	v_mov_b32_e32 v142, v0
	v_mov_b32_e32 v143, v0
	v_mov_b32_e32 v152, v0
	v_mov_b32_e32 v153, v0
	v_mov_b32_e32 v154, v0
	v_mov_b32_e32 v155, v0
	v_mov_b32_e32 v156, v0
	v_mov_b32_e32 v157, v0
	v_mov_b32_e32 v158, v0
	v_mov_b32_e32 v159, v0
	s_waitcnt vmcnt(0)
.LBB0_221:
	ds_read_b128 v[48:51], v208
	ds_read_b128 v[52:55], v208 offset:1024
	ds_read_b128 v[72:75], v208 offset:2048
	ds_read_b128 v[76:79], v208 offset:3072
	ds_read_b128 v[88:91], v209
	ds_read_b128 v[92:95], v209 offset:1024
	ds_read_b128 v[112:115], v209 offset:2048
	ds_read_b128 v[116:119], v209 offset:3072
	s_add_u32 s10, s6, 0xfffc0080
	s_addc_u32 s11, s7, -1
	s_cmp_eq_u32 s37, 12
	s_cselect_b32 s31, s5, s11
	s_cselect_b32 s30, s25, s10
	s_cselect_b32 s11, s23, s36
	s_cselect_b32 s10, s34, s35
	v_lshl_add_u64 v[226:227], s[6:7], 0, v[178:179]
	s_add_i32 m0, s40, 0xc000
	ds_read_b128 v[184:187], v210
	ds_read_b128 v[188:191], v210 offset:1024
	ds_read_b128 v[192:195], v210 offset:2048
	ds_read_b128 v[196:199], v210 offset:3072
	ds_read_b128 v[200:203], v210 offset:4096
	ds_read_b128 v[214:217], v210 offset:5120
	ds_read_b128 v[218:221], v210 offset:6144
	ds_read_b128 v[222:225], v210 offset:7168
	global_load_lds_dwordx4 v[226:227], off
	v_lshl_add_u64 v[226:227], s[6:7], 0, v[176:177]
	s_add_i32 m0, s40, 0xe000
	s_nop 0
	global_load_lds_dwordx4 v[226:227], off
	s_waitcnt vmcnt(8)
	s_waitcnt lgkmcnt(0)
	s_barrier
; #define PG8_STAGE(bufoff, gbase, voff) do { _Pragma("unroll") for (int _i = 0; _i < 2; ++_i) \
;         __builtin_amdgcn_global_load_lds((const unsigned*)((const char*)(gbase) + (voff)[_i]), (PG8_LAS unsigned*)(lds + (bufoff) + ldsw + _i * 8192), 16, 0, 0); } while (0)
; #define PG8_LDA(dst, b, h) do { _Pragma("unroll") for (int m = 0; m < 4; ++m) _Pragma("unroll") for (int k = 0; k < 2; ++k) dst[m][k] = *(const PG8_LAS bf16x8*)(lds + PG8_SA(b, h) + aoff + m * 2048 + k * 1024); } while (0)
; #define PG8_MMA(ai, bj, At, Bt) do { __builtin_amdgcn_s_setprio(1); _Pragma("unroll") for (int m = 0; m < 4; ++m) _Pragma("unroll") for (int n = 0; n < 2; ++n) _Pragma("unroll") for (int k = 0; k < 2; ++k) \
;         acc[ai][bj][m][n] = __builtin_amdgcn_mfma_f32_16x16x32_bf16(Bt[n][k], At[m][k], acc[ai][bj][m][n], 0, 0, 0); __builtin_amdgcn_s_setprio(0); } while (0)
; #define PG8_WAIT_V(n) asm volatile("s_waitcnt vmcnt(" #n ")" ::: "memory")
; #define PG8_WAIT_L(n) asm volatile("s_waitcnt lgkmcnt(" #n ")" ::: "memory")
; #define PG8_BAR __builtin_amdgcn_s_barrier()
; #define PG8_SCHED __builtin_amdgcn_sched_barrier(0)
; template <class Epi, class Sched, bool ALIGN_EPI = false, bool SP2 = false>
; __device__ __forceinline__ void gemm_phase(PG8_LAS unsigned char* lds, const Gemm g, const Sched& S, const Epi& E, int wave0) {
;     ...
;             PG8_WAIT_V(8); PG8_WAIT_L(0); PG8_BAR; PG8_MMA(0, 0, At, B0); PG8_MMA(0, 1, At, B1); PG8_BAR; PG8_SCHED;
;             PG8_LDA(At, 0, 1); PG8_STAGE(PG8_SB(0, 0), b2, voffB); PG8_STAGE(PG8_SB(0, 1), b2 + hstep, voffB); PG8_STAGE(PG8_SA(0, 0), a2, voffA);
;             PG8_WAIT_V(8); PG8_WAIT_L(0); PG8_BAR; PG8_MMA(1, 0, At, B0); PG8_MMA(1, 1, At, B1); PG8_BAR; PG8_SCHED;
	s_setprio 1
	s_waitcnt lgkmcnt(0)
	v_mfma_f32_16x16x32_bf16 v[156:159], v[48:51], v[184:187], v[156:159]
	v_mfma_f32_16x16x32_bf16 v[152:155], v[72:75], v[184:187], v[152:155]
	v_mfma_f32_16x16x32_bf16 v[140:143], v[48:51], v[192:195], v[140:143]
	v_mfma_f32_16x16x32_bf16 v[136:139], v[72:75], v[192:195], v[136:139]
	v_mfma_f32_16x16x32_bf16 v[124:127], v[48:51], v[200:203], v[124:127]
	v_mfma_f32_16x16x32_bf16 v[120:123], v[72:75], v[200:203], v[120:123]
	v_mfma_f32_16x16x32_bf16 v[100:103], v[48:51], v[218:221], v[100:103]
	v_mfma_f32_16x16x32_bf16 v[96:99], v[72:75], v[218:221], v[96:99]
	v_mfma_f32_16x16x32_bf16 v[156:159], v[52:55], v[188:191], v[156:159]
	v_mfma_f32_16x16x32_bf16 v[152:155], v[76:79], v[188:191], v[152:155]
	v_mfma_f32_16x16x32_bf16 v[140:143], v[52:55], v[196:199], v[140:143]
	v_mfma_f32_16x16x32_bf16 v[136:139], v[76:79], v[196:199], v[136:139]
	v_mfma_f32_16x16x32_bf16 v[124:127], v[52:55], v[214:217], v[124:127]
	v_mfma_f32_16x16x32_bf16 v[120:123], v[76:79], v[214:217], v[120:123]
	v_mfma_f32_16x16x32_bf16 v[100:103], v[52:55], v[222:225], v[100:103]
	v_mfma_f32_16x16x32_bf16 v[96:99], v[76:79], v[222:225], v[96:99]
	s_setprio 0
	s_setprio 1
	v_mfma_f32_16x16x32_bf16 v[148:151], v[88:91], v[184:187], v[148:151]
	v_mfma_f32_16x16x32_bf16 v[144:147], v[112:115], v[184:187], v[144:147]
	v_mfma_f32_16x16x32_bf16 v[132:135], v[88:91], v[192:195], v[132:135]
	v_mfma_f32_16x16x32_bf16 v[128:131], v[112:115], v[192:195], v[128:131]
	v_mfma_f32_16x16x32_bf16 v[108:111], v[88:91], v[200:203], v[108:111]
	v_mfma_f32_16x16x32_bf16 v[104:107], v[112:115], v[200:203], v[104:107]
	v_mfma_f32_16x16x32_bf16 v[84:87], v[88:91], v[218:221], v[84:87]
	v_mfma_f32_16x16x32_bf16 v[80:83], v[112:115], v[218:221], v[80:83]
	v_mfma_f32_16x16x32_bf16 v[148:151], v[92:95], v[188:191], v[148:151]
	v_mfma_f32_16x16x32_bf16 v[144:147], v[116:119], v[188:191], v[144:147]
	v_mfma_f32_16x16x32_bf16 v[132:135], v[92:95], v[196:199], v[132:135]
	v_mfma_f32_16x16x32_bf16 v[128:131], v[116:119], v[196:199], v[128:131]
	v_mfma_f32_16x16x32_bf16 v[108:111], v[92:95], v[214:217], v[108:111]
	v_mfma_f32_16x16x32_bf16 v[104:107], v[116:119], v[214:217], v[104:107]
	v_mfma_f32_16x16x32_bf16 v[84:87], v[92:95], v[222:225], v[84:87]
	v_mfma_f32_16x16x32_bf16 v[80:83], v[116:119], v[222:225], v[80:83]
	s_setprio 0
	s_barrier
	s_add_i32 s56, s50, s33
	v_lshl_add_u64 v[226:227], s[10:11], 0, v[162:163]
	s_mov_b32 m0, s56
	ds_read_b128 v[184:187], v210 offset:16384
	ds_read_b128 v[188:191], v210 offset:17408
	ds_read_b128 v[192:195], v210 offset:18432
	ds_read_b128 v[196:199], v210 offset:19456
	ds_read_b128 v[200:203], v210 offset:20480
	ds_read_b128 v[214:217], v210 offset:21504
	ds_read_b128 v[218:221], v210 offset:22528
	ds_read_b128 v[222:225], v210 offset:23552
	global_load_lds_dwordx4 v[226:227], off
	s_add_i32 m0, s56, 0x2000
	s_add_u32 s56, s10, 0x40000
	v_lshl_add_u64 v[228:229], s[10:11], 0, v[166:167]
	s_addc_u32 s57, s11, 0
	s_add_i32 s58, s51, s33
	global_load_lds_dwordx4 v[228:229], off
	v_lshl_add_u64 v[230:231], s[56:57], 0, v[162:163]
	s_mov_b32 m0, s58
	v_lshl_add_u64 v[232:233], s[30:31], 0, v[164:165]
	global_load_lds_dwordx4 v[230:231], off
	v_lshl_add_u64 v[230:231], s[56:57], 0, v[166:167]
	s_add_i32 m0, s58, 0x2000
	s_nop 0
	global_load_lds_dwordx4 v[230:231], off
	v_lshl_add_u64 v[230:231], s[30:31], 0, v[160:161]
	s_mov_b32 m0, s40
	s_nop 0
	global_load_lds_dwordx4 v[230:231], off
	s_mov_b32 m0, s41
	s_nop 0
	global_load_lds_dwordx4 v[232:233], off
	s_waitcnt vmcnt(8)
	s_waitcnt lgkmcnt(0)
	s_barrier
	s_setprio 1
	s_waitcnt lgkmcnt(0)
	v_mfma_f32_16x16x32_bf16 v[68:71], v[48:51], v[184:187], v[68:71]
	v_mfma_f32_16x16x32_bf16 v[64:67], v[72:75], v[184:187], v[64:67]
	v_mfma_f32_16x16x32_bf16 v[44:47], v[48:51], v[192:195], v[44:47]
	v_mfma_f32_16x16x32_bf16 v[40:43], v[72:75], v[192:195], v[40:43]
	v_mfma_f32_16x16x32_bf16 v[28:31], v[48:51], v[200:203], v[28:31]
	v_mfma_f32_16x16x32_bf16 v[24:27], v[72:75], v[200:203], v[24:27]
	v_mfma_f32_16x16x32_bf16 v[12:15], v[48:51], v[218:221], v[12:15]
	v_mfma_f32_16x16x32_bf16 v[8:11], v[72:75], v[218:221], v[8:11]
	v_mfma_f32_16x16x32_bf16 v[68:71], v[52:55], v[188:191], v[68:71]
	v_mfma_f32_16x16x32_bf16 v[64:67], v[76:79], v[188:191], v[64:67]
	v_mfma_f32_16x16x32_bf16 v[44:47], v[52:55], v[196:199], v[44:47]
	v_mfma_f32_16x16x32_bf16 v[40:43], v[76:79], v[196:199], v[40:43]
	v_mfma_f32_16x16x32_bf16 v[28:31], v[52:55], v[214:217], v[28:31]
	v_mfma_f32_16x16x32_bf16 v[24:27], v[76:79], v[214:217], v[24:27]
	v_mfma_f32_16x16x32_bf16 v[12:15], v[52:55], v[222:225], v[12:15]
	v_mfma_f32_16x16x32_bf16 v[8:11], v[76:79], v[222:225], v[8:11]
	s_setprio 0
	s_setprio 1
	v_mfma_f32_16x16x32_bf16 v[36:39], v[88:91], v[192:195], v[36:39]
	v_mfma_f32_16x16x32_bf16 v[32:35], v[112:115], v[192:195], v[32:35]
	v_mfma_f32_16x16x32_bf16 v[20:23], v[88:91], v[200:203], v[20:23]
	v_mfma_f32_16x16x32_bf16 v[16:19], v[112:115], v[200:203], v[16:19]
	v_mfma_f32_16x16x32_bf16 v[4:7], v[88:91], v[218:221], v[4:7]
	v_mfma_f32_16x16x32_bf16 v[0:3], v[112:115], v[218:221], v[0:3]
	v_mfma_f32_16x16x32_bf16 v[48:51], v[88:91], v[184:187], v[60:63]
	v_mfma_f32_16x16x32_bf16 v[52:55], v[112:115], v[184:187], v[56:59]
	v_mfma_f32_16x16x32_bf16 v[36:39], v[92:95], v[196:199], v[36:39]
	v_mfma_f32_16x16x32_bf16 v[32:35], v[116:119], v[196:199], v[32:35]
	v_mfma_f32_16x16x32_bf16 v[20:23], v[92:95], v[214:217], v[20:23]
	v_mfma_f32_16x16x32_bf16 v[16:19], v[116:119], v[214:217], v[16:19]
	v_mfma_f32_16x16x32_bf16 v[4:7], v[92:95], v[222:225], v[4:7]
	v_mfma_f32_16x16x32_bf16 v[0:3], v[116:119], v[222:225], v[0:3]
	v_mfma_f32_16x16x32_bf16 v[48:51], v[92:95], v[188:191], v[48:51]
	v_mfma_f32_16x16x32_bf16 v[52:55], v[116:119], v[188:191], v[52:55]
	s_setprio 0
	s_barrier
; #define PG8_STAGE(bufoff, gbase, voff) do { _Pragma("unroll") for (int _i = 0; _i < 2; ++_i) \
;         __builtin_amdgcn_global_load_lds((const unsigned*)((const char*)(gbase) + (voff)[_i]), (PG8_LAS unsigned*)(lds + (bufoff) + ldsw + _i * 8192), 16, 0, 0); } while (0)
; #define PG8_LDA(dst, b, h) do { _Pragma("unroll") for (int m = 0; m < 4; ++m) _Pragma("unroll") for (int k = 0; k < 2; ++k) dst[m][k] = *(const PG8_LAS bf16x8*)(lds + PG8_SA(b, h) + aoff + m * 2048 + k * 1024); } while (0)
; #define PG8_LDB(dst, b, h) do { _Pragma("unroll") for (int n = 0; n < 2; ++n) _Pragma("unroll") for (int k = 0; k < 2; ++k) dst[n][k] = *(const PG8_LAS bf16x8*)(lds + PG8_SB(b, h) + boff + n * 2048 + k * 1024); } while (0)
; #define PG8_MMA(ai, bj, At, Bt) do { __builtin_amdgcn_s_setprio(1); _Pragma("unroll") for (int m = 0; m < 4; ++m) _Pragma("unroll") for (int n = 0; n < 2; ++n) _Pragma("unroll") for (int k = 0; k < 2; ++k) \
;         acc[ai][bj][m][n] = __builtin_amdgcn_mfma_f32_16x16x32_bf16(Bt[n][k], At[m][k], acc[ai][bj][m][n], 0, 0, 0); __builtin_amdgcn_s_setprio(0); } while (0)
; #define PG8_WAIT_V(n) asm volatile("s_waitcnt vmcnt(" #n ")" ::: "memory")
; #define PG8_WAIT_L(n) asm volatile("s_waitcnt lgkmcnt(" #n ")" ::: "memory")
; #define PG8_BAR __builtin_amdgcn_s_barrier()
; #define PG8_SCHED __builtin_amdgcn_sched_barrier(0)
; template <class Epi, class Sched, bool ALIGN_EPI = false, bool SP2 = false>
; __device__ __forceinline__ void gemm_phase(PG8_LAS unsigned char* lds, const Gemm g, const Sched& S, const Epi& E, int wave0) {
;     ...
;             PG8_LDB(B0, 1, 0); PG8_LDB(B1, 1, 1); PG8_SCHED; PG8_LDA(At, 1, 0); PG8_STAGE(PG8_SA(0, 1), a2 + hstepA, voffA);
;             PG8_WAIT_V(8); PG8_WAIT_L(0); PG8_BAR; PG8_MMA(0, 0, At, B0); PG8_MMA(0, 1, At, B1); PG8_BAR; PG8_SCHED;
	s_add_i32 s56, 0, 0x18000
	s_add_i32 s57, 0, 0x1c000
	v_add_u32_e32 v76, s56, v206
	v_add_u32_e32 v116, s57, v206
	ds_read_b128 v[56:59], v76
	ds_read_b128 v[60:63], v76 offset:1024
	ds_read_b128 v[72:75], v76 offset:2048
	ds_read_b128 v[76:79], v76 offset:3072
	ds_read_b128 v[88:91], v116
	ds_read_b128 v[92:95], v116 offset:1024
	ds_read_b128 v[112:115], v116 offset:2048
	ds_read_b128 v[116:119], v116 offset:3072
	s_add_u32 s30, s30, 0x40000
	s_addc_u32 s31, s31, 0
	s_mov_b32 m0, s42
	v_lshl_add_u64 v[234:235], s[30:31], 0, v[160:161]
	ds_read_b128 v[184:187], v210 offset:32768
	ds_read_b128 v[188:191], v210 offset:33792
	ds_read_b128 v[192:195], v210 offset:34816
	ds_read_b128 v[196:199], v210 offset:35840
	ds_read_b128 v[200:203], v210 offset:36864
	ds_read_b128 v[214:217], v210 offset:37888
	ds_read_b128 v[218:221], v210 offset:38912
	ds_read_b128 v[222:225], v210 offset:39936
	global_load_lds_dwordx4 v[234:235], off
	v_lshl_add_u64 v[234:235], s[30:31], 0, v[164:165]
	s_mov_b32 m0, s43
	s_nop 0
	global_load_lds_dwordx4 v[234:235], off
	s_waitcnt vmcnt(8)
	s_waitcnt lgkmcnt(0)
	s_barrier
	s_setprio 1
	s_waitcnt lgkmcnt(0)
	v_mfma_f32_16x16x32_bf16 v[156:159], v[56:59], v[184:187], v[156:159]
	v_mfma_f32_16x16x32_bf16 v[152:155], v[72:75], v[184:187], v[152:155]
	v_mfma_f32_16x16x32_bf16 v[140:143], v[56:59], v[192:195], v[140:143]
	v_mfma_f32_16x16x32_bf16 v[136:139], v[72:75], v[192:195], v[136:139]
	v_mfma_f32_16x16x32_bf16 v[124:127], v[56:59], v[200:203], v[124:127]
	v_mfma_f32_16x16x32_bf16 v[120:123], v[72:75], v[200:203], v[120:123]
	v_mfma_f32_16x16x32_bf16 v[100:103], v[56:59], v[218:221], v[100:103]
	v_mfma_f32_16x16x32_bf16 v[96:99], v[72:75], v[218:221], v[96:99]
	v_mfma_f32_16x16x32_bf16 v[156:159], v[60:63], v[188:191], v[156:159]
	v_mfma_f32_16x16x32_bf16 v[152:155], v[76:79], v[188:191], v[152:155]
	v_mfma_f32_16x16x32_bf16 v[140:143], v[60:63], v[196:199], v[140:143]
	v_mfma_f32_16x16x32_bf16 v[136:139], v[76:79], v[196:199], v[136:139]
	v_mfma_f32_16x16x32_bf16 v[124:127], v[60:63], v[214:217], v[124:127]
	v_mfma_f32_16x16x32_bf16 v[120:123], v[76:79], v[214:217], v[120:123]
	v_mfma_f32_16x16x32_bf16 v[100:103], v[60:63], v[222:225], v[100:103]
	v_mfma_f32_16x16x32_bf16 v[96:99], v[76:79], v[222:225], v[96:99]
	s_setprio 0
	s_setprio 1
	v_mfma_f32_16x16x32_bf16 v[148:151], v[88:91], v[184:187], v[148:151]
	v_mfma_f32_16x16x32_bf16 v[144:147], v[112:115], v[184:187], v[144:147]
	v_mfma_f32_16x16x32_bf16 v[132:135], v[88:91], v[192:195], v[132:135]
	v_mfma_f32_16x16x32_bf16 v[128:131], v[112:115], v[192:195], v[128:131]
	v_mfma_f32_16x16x32_bf16 v[108:111], v[88:91], v[200:203], v[108:111]
	v_mfma_f32_16x16x32_bf16 v[104:107], v[112:115], v[200:203], v[104:107]
	v_mfma_f32_16x16x32_bf16 v[84:87], v[88:91], v[218:221], v[84:87]
	v_mfma_f32_16x16x32_bf16 v[80:83], v[112:115], v[218:221], v[80:83]
	v_mfma_f32_16x16x32_bf16 v[148:151], v[92:95], v[188:191], v[148:151]
	v_mfma_f32_16x16x32_bf16 v[144:147], v[116:119], v[188:191], v[144:147]
	v_mfma_f32_16x16x32_bf16 v[132:135], v[92:95], v[196:199], v[132:135]
	v_mfma_f32_16x16x32_bf16 v[128:131], v[116:119], v[196:199], v[128:131]
	v_mfma_f32_16x16x32_bf16 v[108:111], v[92:95], v[214:217], v[108:111]
	v_mfma_f32_16x16x32_bf16 v[104:107], v[116:119], v[214:217], v[104:107]
	v_mfma_f32_16x16x32_bf16 v[84:87], v[92:95], v[222:225], v[84:87]
	v_mfma_f32_16x16x32_bf16 v[80:83], v[116:119], v[222:225], v[80:83]
	s_setprio 0
	s_barrier
; #define PG8_STAGE(bufoff, gbase, voff) do { _Pragma("unroll") for (int _i = 0; _i < 2; ++_i) \
;         __builtin_amdgcn_global_load_lds((const unsigned*)((const char*)(gbase) + (voff)[_i]), (PG8_LAS unsigned*)(lds + (bufoff) + ldsw + _i * 8192), 16, 0, 0); } while (0)
; #define PG8_LDA(dst, b, h) do { _Pragma("unroll") for (int m = 0; m < 4; ++m) _Pragma("unroll") for (int k = 0; k < 2; ++k) dst[m][k] = *(const PG8_LAS bf16x8*)(lds + PG8_SA(b, h) + aoff + m * 2048 + k * 1024); } while (0)
; #define PG8_MMA(ai, bj, At, Bt) do { __builtin_amdgcn_s_setprio(1); _Pragma("unroll") for (int m = 0; m < 4; ++m) _Pragma("unroll") for (int n = 0; n < 2; ++n) _Pragma("unroll") for (int k = 0; k < 2; ++k) \
;         acc[ai][bj][m][n] = __builtin_amdgcn_mfma_f32_16x16x32_bf16(Bt[n][k], At[m][k], acc[ai][bj][m][n], 0, 0, 0); __builtin_amdgcn_s_setprio(0); } while (0)
; #define PG8_WAIT_V(n) asm volatile("s_waitcnt vmcnt(" #n ")" ::: "memory")
; #define PG8_WAIT_L(n) asm volatile("s_waitcnt lgkmcnt(" #n ")" ::: "memory")
; #define PG8_BAR __builtin_amdgcn_s_barrier()
; #define PG8_SCHED __builtin_amdgcn_sched_barrier(0)
; template <class Epi, class Sched, bool ALIGN_EPI = false, bool SP2 = false>
; __device__ __forceinline__ void gemm_phase(PG8_LAS unsigned char* lds, const Gemm g, const Sched& S, const Epi& E, int wave0) {
;     ...
;         for (int t = 0; t < nt; t += 2) {
;     ...
;             PG8_LDA(At, 1, 1); PG8_STAGE(PG8_SB(1, 0), b3, voffB); PG8_STAGE(PG8_SB(1, 1), b3 + hstep, voffB); PG8_STAGE(PG8_SA(1, 0), a3, voffA);
;             PG8_WAIT_V(8); PG8_WAIT_L(0); PG8_BAR; PG8_MMA(1, 0, At, B0); PG8_MMA(1, 1, At, B1); PG8_BAR; PG8_SCHED;
;     ...
;         if constexpr (ALIGN_EPI) { if (wr == 0) PG8_BAR; }
	s_add_i32 s30, s56, s33
	v_lshl_add_u64 v[226:227], v[226:227], 0, s[18:19]
	s_mov_b32 m0, s30
	ds_read_b128 v[184:187], v210 offset:49152
	ds_read_b128 v[188:191], v210 offset:50176
	ds_read_b128 v[192:195], v210 offset:51200
	ds_read_b128 v[196:199], v210 offset:52224
	ds_read_b128 v[200:203], v210 offset:53248
	ds_read_b128 v[214:217], v210 offset:54272
	ds_read_b128 v[218:221], v210 offset:55296
	ds_read_b128 v[222:225], v210 offset:56320
	global_load_lds_dwordx4 v[226:227], off
	s_add_i32 m0, s30, 0x2000
	s_add_u32 s10, s10, 0x40080
	v_lshl_add_u64 v[226:227], v[228:229], 0, s[18:19]
	s_addc_u32 s11, s11, 0
	s_add_i32 s30, s57, s33
	global_load_lds_dwordx4 v[226:227], off
	v_lshl_add_u64 v[226:227], s[10:11], 0, v[162:163]
	s_mov_b32 m0, s30
	s_nop 0
	global_load_lds_dwordx4 v[226:227], off
	v_lshl_add_u64 v[226:227], s[10:11], 0, v[166:167]
	s_add_i32 m0, s30, 0x2000
	s_nop 0
	global_load_lds_dwordx4 v[226:227], off
	v_lshl_add_u64 v[226:227], v[230:231], 0, s[18:19]
	s_mov_b32 m0, s44
	s_nop 0
	global_load_lds_dwordx4 v[226:227], off
	v_lshl_add_u64 v[226:227], v[232:233], 0, s[18:19]
	s_mov_b32 m0, s45
	s_nop 0
	global_load_lds_dwordx4 v[226:227], off
	s_waitcnt vmcnt(8)
	s_waitcnt lgkmcnt(0)
	s_barrier
	s_setprio 1
	s_waitcnt lgkmcnt(0)
	v_mfma_f32_16x16x32_bf16 v[68:71], v[56:59], v[184:187], v[68:71]
	v_mfma_f32_16x16x32_bf16 v[64:67], v[72:75], v[184:187], v[64:67]
	v_mfma_f32_16x16x32_bf16 v[44:47], v[56:59], v[192:195], v[44:47]
	v_mfma_f32_16x16x32_bf16 v[40:43], v[72:75], v[192:195], v[40:43]
	v_mfma_f32_16x16x32_bf16 v[28:31], v[56:59], v[200:203], v[28:31]
	v_mfma_f32_16x16x32_bf16 v[24:27], v[72:75], v[200:203], v[24:27]
	v_mfma_f32_16x16x32_bf16 v[12:15], v[56:59], v[218:221], v[12:15]
	v_mfma_f32_16x16x32_bf16 v[8:11], v[72:75], v[218:221], v[8:11]
	v_mfma_f32_16x16x32_bf16 v[68:71], v[60:63], v[188:191], v[68:71]
	v_mfma_f32_16x16x32_bf16 v[64:67], v[76:79], v[188:191], v[64:67]
	v_mfma_f32_16x16x32_bf16 v[44:47], v[60:63], v[196:199], v[44:47]
	v_mfma_f32_16x16x32_bf16 v[40:43], v[76:79], v[196:199], v[40:43]
	v_mfma_f32_16x16x32_bf16 v[28:31], v[60:63], v[214:217], v[28:31]
	v_mfma_f32_16x16x32_bf16 v[24:27], v[76:79], v[214:217], v[24:27]
	v_mfma_f32_16x16x32_bf16 v[12:15], v[60:63], v[222:225], v[12:15]
	v_mfma_f32_16x16x32_bf16 v[8:11], v[76:79], v[222:225], v[8:11]
	s_setprio 0
	s_setprio 1
	v_mfma_f32_16x16x32_bf16 v[48:51], v[88:91], v[184:187], v[48:51]
	v_mfma_f32_16x16x32_bf16 v[60:63], v[92:95], v[188:191], v[48:51]
	v_mfma_f32_16x16x32_bf16 v[48:51], v[112:115], v[184:187], v[52:55]
	v_mfma_f32_16x16x32_bf16 v[36:39], v[88:91], v[192:195], v[36:39]
	v_mfma_f32_16x16x32_bf16 v[32:35], v[112:115], v[192:195], v[32:35]
	v_mfma_f32_16x16x32_bf16 v[20:23], v[88:91], v[200:203], v[20:23]
	v_mfma_f32_16x16x32_bf16 v[16:19], v[112:115], v[200:203], v[16:19]
	v_mfma_f32_16x16x32_bf16 v[4:7], v[88:91], v[218:221], v[4:7]
	v_mfma_f32_16x16x32_bf16 v[0:3], v[112:115], v[218:221], v[0:3]
	v_mfma_f32_16x16x32_bf16 v[56:59], v[116:119], v[188:191], v[48:51]
	v_mfma_f32_16x16x32_bf16 v[36:39], v[92:95], v[196:199], v[36:39]
	v_mfma_f32_16x16x32_bf16 v[32:35], v[116:119], v[196:199], v[32:35]
	v_mfma_f32_16x16x32_bf16 v[20:23], v[92:95], v[214:217], v[20:23]
	v_mfma_f32_16x16x32_bf16 v[16:19], v[116:119], v[214:217], v[16:19]
	v_mfma_f32_16x16x32_bf16 v[4:7], v[92:95], v[222:225], v[4:7]
	v_mfma_f32_16x16x32_bf16 v[0:3], v[116:119], v[222:225], v[0:3]
	s_setprio 0
	s_barrier
	s_add_i32 s37, s37, 2
	s_add_u32 s35, s35, 0x100
	s_addc_u32 s36, s36, 0
	s_add_u32 s6, s6, 0x100
	s_addc_u32 s7, s7, 0
	s_cmp_gt_u32 s37, 13
	s_cbranch_scc0 .LBB0_221
	s_and_b64 vcc, exec, s[20:21]
	s_cbranch_vccz .LBB0_224
	s_barrier

; #define GAS __attribute__((address_space(1)))
; __device__ __forceinline__ void c_phase(const bf16_t* Z, bf16_t* MIX, float* LSE, ldsp lds, int pi, int bx, int G, unsigned& gt, int wave0, int ucount) {
;     ...
;         C_DEC(u, b, hp, rs, blk);
;         const int head = 2 * hp + hsel, q0 = 128 * blk + 32 * gq, ql = q0 + r32;
;         const int kt0 = blk >= 1 ? 2 * blk - 2 : 0, kt1 = 2 * blk + 1;
;         const bf16_t* kvp = C_KVP(b, hp, rs);
;         const bool has_next = u + 1 < uend;
;         const int un = has_next ? u + 1 : u;
;         C_DEC(un, bn, hpn, rsn, blkn);
;         const int kt0n = blkn >= 1 ? 2 * blkn - 2 : 0;
;         const bf16_t* kvpn = C_KVP(bn, hpn, rsn) + kt0n * tstride;
;         bf16x8 qr[4]; q_load(qr, C_QROW(b, hp, rs, blk), hi);
;         GAS float* lsep = (GAS float*)(LSE + ((size_t)b * T + (size_t)q0 * dil + rs) * 16 + head + llane);
;         bf16_t* orow = MIX + ((size_t)b * T + (size_t)q0 * dil + rs) * 1024 + head * 64 + olane;
;         const size_t ostep = (size_t)8 * dil * 1024;
;         u32x4 orun[4] = {z4, z4, z4, z4}; float lse_old = 0.f;
;         float m = 0.f, l = 0.f; bool started = false;
;         f32x16 o[2], negm; splat16(negm, 0.f);
;         splat16(o[0], 0.f); splat16(o[1], 0.f);
.LBB0_1034:
	s_ashr_i32 s0, s1, s33
	v_readlane_b32 s36, v254, 18
	s_and_b32 s36, s0, s35
	s_lshr_b32 s0, s1, 4
	s_and_b32 s9, s1, s34
	s_and_b32 s0, s0, 14
	v_readlane_b32 s8, v254, 16
	s_add_i32 s14, s0, s8
	s_lshl_b32 s10, s9, 7
	v_readlane_b32 s8, v254, 41
	s_lshl_b32 s87, s9, 1
	s_ashr_i32 s12, s1, 8
	s_add_i32 s8, s10, s8
	s_add_i32 s11, s87, -2
	s_cmp_lg_u32 s9, 0
	s_cselect_b32 s84, s11, 0
	s_or_b32 s78, s87, 1
	s_add_i32 s86, s1, 1
	v_readlane_b32 s40, v254, 22
	v_readlane_b32 s41, v254, 23
	s_cmp_lt_i32 s86, s65
	s_mul_i32 s11, s12, 48
	s_cselect_b64 s[40:41], -1, 0
	s_cmp_ge_i32 s86, s65
	s_cselect_b64 s[92:93], -1, 0
	s_add_i32 s16, s14, s11
	s_ashr_i32 s9, s8, 31
	v_readlane_b32 s13, v254, 40
	s_ashr_i32 s17, s16, 31
	s_lshl_b64 s[18:19], s[8:9], s13
	s_add_u32 s18, s18, s36
	s_addc_u32 s19, s19, 0
	s_lshl_b64 s[16:17], s[16:17], 19
	s_lshl_b64 s[20:21], s[18:19], 7
	v_lshl_add_u64 v[16:17], v[188:189], 0, s[16:17]
	v_lshl_add_u64 v[16:17], v[16:17], 0, s[20:21]
	global_load_dwordx4 v[160:163], v[16:17], off
	global_load_dwordx4 v[164:167], v[16:17], off offset:32
	global_load_dwordx4 v[168:171], v[16:17], off offset:64
	global_load_dwordx4 v[172:175], v[16:17], off offset:96
	s_ashr_i32 s13, s12, 31
	s_lshl_b64 s[12:13], s[12:13], 12
	s_add_u32 s12, s18, s12
	s_addc_u32 s13, s19, s13
	s_lshl_b64 s[16:17], s[12:13], 6
	s_add_u32 s9, s4, s16
	s_addc_u32 s18, s29, s17
	s_ashr_i32 s15, s14, 31
	s_lshl_b64 s[16:17], s[14:15], 2
	s_add_u32 s16, s9, s16
	s_addc_u32 s17, s18, s17
	s_lshl_b64 s[12:13], s[12:13], 11
	v_readlane_b32 s9, v255, 18
	s_add_u32 s9, s9, s12
	v_readlane_b32 s12, v255, 19
	s_addc_u32 s15, s12, s13
	s_lshl_b32 s12, s14, 6
	s_ashr_i32 s13, s12, 31
	s_lshl_b64 s[12:13], s[12:13], 1
	s_add_u32 s12, s9, s12
	s_addc_u32 s13, s15, s13
	s_waitcnt vmcnt(12)
	v_mov_b32_e32 v191, v177
	v_mov_b64_e32 v[62:63], v[14:15]
	v_mov_b64_e32 v[46:47], v[14:15]
	v_mov_b64_e32 v[30:31], v[14:15]
	v_readlane_b32 s37, v254, 19
	v_lshl_add_u64 v[194:195], v[182:183], 2, s[16:17]
	v_lshl_add_u64 v[192:193], s[12:13], 0, v[190:191]
	v_mov_b64_e32 v[60:61], v[12:13]
	v_mov_b64_e32 v[58:59], v[10:11]
	v_mov_b64_e32 v[56:57], v[8:9]
	v_mov_b64_e32 v[54:55], v[6:7]
	v_mov_b64_e32 v[52:53], v[4:5]
	v_mov_b64_e32 v[50:51], v[2:3]
	v_mov_b64_e32 v[48:49], v[0:1]
	v_mov_b64_e32 v[44:45], v[12:13]
	v_mov_b64_e32 v[42:43], v[10:11]
	v_mov_b64_e32 v[40:41], v[8:9]
	v_mov_b64_e32 v[38:39], v[6:7]
	v_mov_b64_e32 v[36:37], v[4:5]
	v_mov_b64_e32 v[34:35], v[2:3]
	v_mov_b64_e32 v[32:33], v[0:1]
	v_mov_b64_e32 v[28:29], v[12:13]
	v_mov_b64_e32 v[26:27], v[10:11]
	v_mov_b64_e32 v[24:25], v[8:9]
	v_mov_b64_e32 v[22:23], v[6:7]
	v_mov_b64_e32 v[20:21], v[4:5]
	v_mov_b64_e32 v[18:19], v[2:3]
	v_mov_b64_e32 v[16:17], v[0:1]
	s_cmp_gt_i32 s84, s78
	v_readlane_b32 s38, v254, 20
	v_readlane_b32 s39, v254, 21
	v_readlane_b32 s42, v254, 24
	v_readlane_b32 s43, v254, 25
	v_readlane_b32 s44, v254, 26
	v_readlane_b32 s45, v254, 27
	v_readlane_b32 s46, v254, 28
	v_readlane_b32 s47, v254, 29
	v_readlane_b32 s48, v254, 30
	v_readlane_b32 s49, v254, 31
	v_readlane_b32 s50, v254, 32
	v_readlane_b32 s51, v254, 33
	s_cbranch_scc1 .LBB0_1074
	s_add_i32 s0, s11, s0
	s_add_i32 s12, s0, 16
	s_ashr_i32 s13, s12, 31
	s_lshl_b64 s[12:13], s[12:13], 19
	s_add_u32 s0, s80, s12
	s_addc_u32 s9, s81, s13
	s_lshl_b64 s[12:13], s[36:37], 7
	s_add_u32 s85, s0, s12
	s_addc_u32 s0, s9, s13
	s_and_b64 s[12:13], s[40:41], exec
	s_cselect_b32 s1, s86, s1
	s_ashr_i32 s9, s1, 8
	s_lshr_b32 s11, s1, 4
	s_mul_i32 s9, s9, 48
	s_and_b32 s11, s11, 14
	s_or_b32 s9, s9, s11
	s_add_i32 s12, s9, 16
	s_ashr_i32 s13, s12, 31
	s_lshl_b64 s[12:13], s[12:13], 19
	s_add_u32 s9, s80, s12
	s_addc_u32 s11, s81, s13
	s_ashr_i32 s12, s1, s33
	s_and_b32 s12, s12, s35
	s_lshl_b32 s12, s12, 7
	s_add_u32 s9, s9, s12
	s_addc_u32 s11, s11, 0
	s_and_b32 s1, s1, s34
	s_lshl_b32 s12, s1, 1
	s_add_i32 s12, s12, -2
	s_mov_b32 s4, s65
	s_cmp_lg_u32 s1, 0
	s_mov_b32 s1, s37
	s_cselect_b32 s36, s12, 0
	v_writelane_b32 v254, s0, 18
	s_waitcnt vmcnt(8)
	v_mov_b32_e32 v144, 0
	s_mov_b32 s95, s34
	v_writelane_b32 v254, s1, 19
	v_writelane_b32 v254, s2, 20
	v_writelane_b32 v254, s3, 21
	v_writelane_b32 v254, s4, 22
	v_writelane_b32 v254, s5, 23
	v_writelane_b32 v254, s6, 24
	v_writelane_b32 v254, s7, 25
	v_writelane_b32 v254, s8, 26
	v_writelane_b32 v254, s9, 27
	v_writelane_b32 v254, s10, 28
	v_writelane_b32 v254, s11, 29
	v_writelane_b32 v254, s12, 30
	v_writelane_b32 v254, s13, 31
	v_writelane_b32 v254, s14, 32
	v_writelane_b32 v254, s15, 33
	s_lshl_b64 s[12:13], s[36:37], s72
	s_lshl_b64 s[12:13], s[12:13], 1
	s_add_u32 s1, s9, s12
	s_addc_u32 s74, s11, s13
	s_or_b32 s75, s8, 31
	s_add_i32 s76, s8, 0xffffff80
	v_readlane_b32 s8, v255, 23
	v_readlane_b32 s9, v255, 24
	v_add_u32_e32 v64, s10, v252
	s_lshl_b32 s73, s84, 6
	v_lshl_add_u64 v[196:197], s[8:9], 1, v[192:193]
	v_readlane_b32 s8, v255, 25
	v_readlane_b32 s9, v255, 26
	s_lshl_b32 s77, s3, 15
	v_subrev_u32_e32 v213, s73, v64
	v_lshl_add_u64 v[198:199], s[8:9], 1, v[192:193]
	v_readlane_b32 s8, v255, 27
	v_readlane_b32 s9, v255, 28
	s_mov_b64 s[88:89], 0
	v_mov_b32_e32 v191, 0
	v_lshl_add_u64 v[200:201], s[8:9], 1, v[192:193]
	v_mov_b32_e32 v181, 0
	v_mov_b32_e32 v180, 0
	v_mov_b32_e32 v145, v144
	v_mov_b32_e32 v146, v144
	v_mov_b32_e32 v147, v144
	v_mov_b32_e32 v148, v144
	v_mov_b32_e32 v149, v144
	v_mov_b32_e32 v150, v144
	v_mov_b32_e32 v151, v144
	v_mov_b32_e32 v152, v144
	v_mov_b32_e32 v153, v144
	v_mov_b32_e32 v154, v144
	v_mov_b32_e32 v155, v144
	v_mov_b32_e32 v156, v144
	v_mov_b32_e32 v157, v144
	v_mov_b32_e32 v158, v144
	v_mov_b32_e32 v159, v144
	s_waitcnt vmcnt(0)

; #define LAS __attribute__((address_space(3)))
; __device__ __forceinline__ int crow(int r, int hi) { return (r & 3) + 8 * (r >> 2) + 4 * hi; }
; __device__ __forceinline__ void qk_tile(f32x16& p0, f32x16& p1, const ldsp Kt, const bf16x8 (&qr)[4], const f32x16& cin, int r32, int hi) {
;     const ldsp kb = Kt + hi * 1024; const int ks = (r32 ^ (2 * hi)) << 4;
; #pragma unroll
;     for (int d0 = 0; d0 < 4; ++d0) {
;         const ldsp kp = kb + d0 * 2048 + (ks ^ (64 * d0));
;         const bf16x8 b0 = *(const LAS bf16x8*)(kp), b1 = *(const LAS bf16x8*)(kp + 512);
;         if (d0 == 0) { p0 = __builtin_amdgcn_mfma_f32_32x32x16_bf16(b0, qr[0], cin, 0, 0, 0); p1 = __builtin_amdgcn_mfma_f32_32x32x16_bf16(b1, qr[0], cin, 0, 0, 0); }
;         else { p0 = __builtin_amdgcn_mfma_f32_32x32x16_bf16(b0, qr[d0], p0, 0, 0, 0); p1 = __builtin_amdgcn_mfma_f32_32x32x16_bf16(b1, qr[d0], p1, 0, 0, 0); }
;     }
;     asm volatile("s_nop 15\n\ts_nop 7" : "+v"(p0), "+v"(p1));
; }
; __device__ __forceinline__ void mask_tile(f32x16& p0, f32x16& p1, int lo, int hq, int hi) {
;     const bool nl = __any(lo > 0), nh = __any(hq < 63);
;     if (nh && nl) {
; #pragma unroll
;         for (int r = 0; r < 16; ++r) { const int kk = crow(r, hi);
;             if (!(kk >= lo && kk <= hq)) p0[r] = NEG_INF;
;             if (!(kk + 32 >= lo && kk + 32 <= hq)) p1[r] = NEG_INF; }
;     } else if (nh) {
;         const int h2 = hq - 4 * hi;
; #pragma unroll
;         for (int r = 0; r < 16; ++r) { const int kc = (r & 3) + 8 * (r >> 2);
;             if (kc > h2) p0[r] = NEG_INF;
;             if (kc + 32 > h2) p1[r] = NEG_INF; }
.LBB0_1038:
	s_and_b32 s79, s77, 0x8000
	s_cmp_gt_i32 s73, s75
	s_cselect_b64 s[8:9], -1, 0
	s_add_i32 s10, s73, 63
	s_cmp_lt_i32 s10, s76
	s_cselect_b64 s[10:11], -1, 0
	s_or_b64 s[8:9], s[8:9], s[10:11]
	s_and_b64 vcc, exec, s[8:9]
	s_cbranch_vccnz .LBB0_1062
	s_add_i32 s33, s94, s79
	v_add_u32_e32 v68, s33, v187
	v_add_u32_e32 v69, v68, v208
	ds_read_b128 v[64:67], v69
	v_add_u32_e32 v176, 0x80, v213
	v_cmp_lt_i32_e32 vcc, 0, v213
	s_cmp_lg_u64 vcc, 0
	v_cmp_gt_i32_e32 vcc, 63, v176
	s_cselect_b64 s[10:11], -1, 0
	s_cmp_eq_u64 vcc, 0
	s_cselect_b64 s[8:9], -1, 0
	s_cmp_lg_u64 vcc, 0
	s_waitcnt lgkmcnt(0)
	v_mfma_f32_32x32x16_bf16 v[112:127], v[64:67], v[160:163], v[48:63]
	ds_read_b128 v[64:67], v69 offset:512
	s_cselect_b64 s[12:13], -1, 0
	s_and_b64 s[12:13], s[10:11], s[12:13]
	s_andn2_b64 vcc, exec, s[12:13]
	s_waitcnt lgkmcnt(0)
	v_mfma_f32_32x32x16_bf16 v[96:111], v[64:67], v[160:163], v[48:63]
	v_xor_b32_e32 v64, 64, v208
	v_add_u32_e32 v69, v68, v64
	ds_read_b128 v[64:67], v69 offset:2048
	s_waitcnt lgkmcnt(0)
	v_mfma_f32_32x32x16_bf16 v[112:127], v[64:67], v[164:167], v[112:127]
	ds_read_b128 v[64:67], v69 offset:2560
	s_waitcnt lgkmcnt(0)
	v_mfma_f32_32x32x16_bf16 v[96:111], v[64:67], v[164:167], v[96:111]
	v_xor_b32_e32 v64, 0x80, v208
	v_add_u32_e32 v69, v68, v64
	ds_read_b128 v[64:67], v69 offset:4096
	s_waitcnt lgkmcnt(0)
	v_mfma_f32_32x32x16_bf16 v[112:127], v[64:67], v[168:171], v[112:127]
	ds_read_b128 v[64:67], v69 offset:4608
	v_xor_b32_e32 v69, 0xc0, v208
	v_add_u32_e32 v72, v68, v69
	ds_read_b128 v[68:71], v72 offset:6144
	s_waitcnt lgkmcnt(1)
	v_mfma_f32_32x32x16_bf16 v[96:111], v[64:67], v[168:171], v[96:111]
	ds_read_b128 v[64:67], v72 offset:6656
	s_waitcnt lgkmcnt(1)
	v_mfma_f32_32x32x16_bf16 v[112:127], v[68:71], v[172:175], v[112:127]
	s_waitcnt lgkmcnt(0)
	v_mfma_f32_32x32x16_bf16 v[96:111], v[64:67], v[172:175], v[96:111]
	s_nop 15
	s_nop 7
	s_cbranch_vccz .LBB0_1046
	s_and_b64 vcc, exec, s[8:9]
	s_cbranch_vccz .LBB0_1073
	s_nop 6
	v_mov_b64_e32 v[64:65], v[112:113]
	s_nop 0
	v_mov_b64_e32 v[80:81], v[96:97]
	s_mov_b64 s[8:9], 0
	s_and_b64 vcc, exec, s[10:11]
	s_mov_b64 s[96:97], 0
	v_mov_b64_e32 v[66:67], v[114:115]
	v_mov_b64_e32 v[68:69], v[116:117]
	v_mov_b64_e32 v[70:71], v[118:119]
	v_mov_b64_e32 v[72:73], v[120:121]
	v_mov_b64_e32 v[74:75], v[122:123]
	v_mov_b64_e32 v[76:77], v[124:125]
	v_mov_b64_e32 v[78:79], v[126:127]
	v_mov_b64_e32 v[82:83], v[98:99]
	v_mov_b64_e32 v[84:85], v[100:101]
	v_mov_b64_e32 v[86:87], v[102:103]
	v_mov_b64_e32 v[88:89], v[104:105]
	v_mov_b64_e32 v[90:91], v[106:107]
	v_mov_b64_e32 v[92:93], v[108:109]
	v_mov_b64_e32 v[94:95], v[110:111]
	s_cbranch_vccz .LBB0_1043
	v_add_u32_e32 v214, v253, v213
	v_cmp_gt_i32_e32 vcc, 1, v214
	v_mov_b32_e32 v95, v111
	s_nop 0
	v_cndmask_b32_e32 v64, v216, v112, vcc
	v_cmp_gt_i32_e32 vcc, 33, v214
	s_nop 1
	v_cndmask_b32_e32 v80, v216, v96, vcc
	v_cmp_gt_i32_e32 vcc, 2, v214
	s_nop 1
	v_cndmask_b32_e32 v65, v216, v113, vcc
	v_cmp_gt_i32_e32 vcc, 34, v214
	s_nop 1
	v_cndmask_b32_e32 v81, v216, v97, vcc
	v_cmp_gt_i32_e32 vcc, 3, v214
	s_nop 1
	v_cndmask_b32_e32 v66, v216, v114, vcc
	v_cmp_gt_i32_e32 vcc, 35, v214
	s_nop 1
	v_cndmask_b32_e32 v82, v216, v98, vcc
	v_cmp_gt_i32_e32 vcc, 4, v214
	s_nop 1
	v_cndmask_b32_e32 v67, v216, v115, vcc
	v_cmp_gt_i32_e32 vcc, 36, v214
	s_nop 1
	v_cndmask_b32_e32 v83, v216, v99, vcc
	v_cmp_gt_i32_e32 vcc, 9, v214
	s_nop 1
	v_cndmask_b32_e32 v68, v216, v116, vcc
	v_cmp_gt_i32_e32 vcc, 41, v214
	s_nop 1
	v_cndmask_b32_e32 v84, v216, v100, vcc
	v_cmp_gt_i32_e32 vcc, 10, v214
	s_nop 1
	v_cndmask_b32_e32 v69, v216, v117, vcc
	v_cmp_gt_i32_e32 vcc, 42, v214
	s_nop 1
	v_cndmask_b32_e32 v85, v216, v101, vcc
	v_cmp_gt_i32_e32 vcc, 11, v214
	s_nop 1
	v_cndmask_b32_e32 v70, v216, v118, vcc
	v_cmp_gt_i32_e32 vcc, 43, v214
	s_nop 1
	v_cndmask_b32_e32 v86, v216, v102, vcc
	v_cmp_gt_i32_e32 vcc, 12, v214
	s_nop 1
	v_cndmask_b32_e32 v71, v216, v119, vcc
	v_cmp_gt_i32_e32 vcc, 44, v214
	s_nop 1
	v_cndmask_b32_e32 v87, v216, v103, vcc
	v_cmp_gt_i32_e32 vcc, 17, v214
	s_nop 1
	v_cndmask_b32_e32 v72, v216, v120, vcc
	v_cmp_gt_i32_e32 vcc, 49, v214
	s_nop 1
	v_cndmask_b32_e32 v88, v216, v104, vcc
	v_cmp_gt_i32_e32 vcc, 18, v214
	s_nop 1
	v_cndmask_b32_e32 v73, v216, v121, vcc
	v_cmp_gt_i32_e32 vcc, 50, v214
	s_nop 1
	v_cndmask_b32_e32 v89, v216, v105, vcc
	v_cmp_gt_i32_e32 vcc, 19, v214
	s_nop 1
	v_cndmask_b32_e32 v74, v216, v122, vcc
	v_cmp_gt_i32_e32 vcc, 51, v214
	s_nop 1
	v_cndmask_b32_e32 v90, v216, v106, vcc
	v_cmp_gt_i32_e32 vcc, 20, v214
	s_nop 1
	v_cndmask_b32_e32 v75, v216, v123, vcc
	v_cmp_gt_i32_e32 vcc, 52, v214
	s_nop 1
	v_cndmask_b32_e32 v91, v216, v107, vcc
	v_cmp_gt_i32_e32 vcc, 25, v214
	s_nop 1
	v_cndmask_b32_e32 v76, v216, v124, vcc
	v_cmp_gt_i32_e32 vcc, 57, v214
	s_nop 1
	v_cndmask_b32_e32 v92, v216, v108, vcc
	v_cmp_gt_i32_e32 vcc, 26, v214
	s_nop 1
	v_cndmask_b32_e32 v77, v216, v125, vcc
	v_cmp_gt_i32_e32 vcc, 58, v214
	s_nop 1
	v_cndmask_b32_e32 v93, v216, v109, vcc
	v_cmp_gt_i32_e32 vcc, 27, v214
	s_nop 1
	v_cndmask_b32_e32 v78, v216, v126, vcc
	v_cmp_gt_i32_e32 vcc, 59, v214
	s_nop 1
	v_cndmask_b32_e32 v94, v216, v110, vcc
	v_cmp_gt_i32_e32 vcc, 28, v214
	s_nop 1
	v_cndmask_b32_e32 v79, v216, v127, vcc
	v_cmp_lt_i32_e32 vcc, 59, v214
	s_and_b64 s[96:97], vcc, exec

; #define LAS __attribute__((address_space(3)))
; #define LDS_WAIT() asm volatile("s_waitcnt lgkmcnt(0)" ::: "memory")
; __device__ __forceinline__ int crow(int r, int hi) { return (r & 3) + 8 * (r >> 2) + 4 * hi; }
; __device__ __forceinline__ void c_phase(const bf16_t* Z, bf16_t* MIX, float* LSE, ldsp lds, int pi, int bx, int G, unsigned& gt, int wave0, int ucount) {
;     ...
;         LDS_WAIT();
;         if (hi == 0) { wsf[r32] = wa; wsf[32 + r32] = wb; }
;         LDS_WAIT();
;         LAS float* stg = (LAS float*)(lds + 65536 + w * 8704);
; #pragma unroll
;         for (int d0 = 0; d0 < 2; ++d0)
; #pragma unroll
;             for (int r = 0; r < 16; ++r) { const int q = crow(r, hi); stg[q * 68 + d0 * 32 + r32] = wsf[32 + q] * o[d0][r]; }
;         LDS_WAIT();
; #pragma unroll
;         for (int i = 0; i < 4; ++i) {
;             const int row = i * 8 + (lane >> 3);
;             const f32x4 x0 = *(const LAS f32x4*)(stg + row * 68 + (lane & 7) * 8), x1 = *(const LAS f32x4*)(stg + row * 68 + (lane & 7) * 8 + 4);
;             float v[8] = {x0[0], x0[1], x0[2], x0[3], x1[0], x1[1], x1[2], x1[3]};
;             if (pi > 0) { const float fa = wsf[row];
; #pragma unroll
;                 for (int k = 0; k < 4; ++k) { const unsigned wd = orun[i][k]; v[2 * k] += fa * __builtin_bit_cast(float, wd << 16); v[2 * k + 1] += fa * __builtin_bit_cast(float, wd & 0xffff0000u); } }
.LBB0_1085:
	s_or_b64 exec, exec, s[8:9]
	s_waitcnt lgkmcnt(0)
	v_add_u32_e32 v48, s5, v186
	s_andn2_b64 vcc, exec, s[82:83]
	ds_read_b128 v[52:55], v48 offset:128
	ds_read_b128 v[56:59], v48 offset:160
	ds_read_b128 v[60:63], v48 offset:192
	ds_read_b128 v[48:51], v48 offset:224
	s_waitcnt lgkmcnt(3)
	v_mul_f32_e32 v32, v32, v52
	v_mul_f32_e32 v33, v33, v53
	v_mul_f32_e32 v34, v34, v54
	v_mul_f32_e32 v35, v35, v55
	v_mul_f32_e32 v16, v16, v52
	v_mul_f32_e32 v17, v17, v53
	v_mul_f32_e32 v18, v18, v54
	v_mul_f32_e32 v19, v19, v55
	s_waitcnt lgkmcnt(2)
	v_mul_f32_e32 v36, v36, v56
	v_mul_f32_e32 v37, v37, v57
	v_mul_f32_e32 v38, v38, v58
	v_mul_f32_e32 v39, v39, v59
	v_mul_f32_e32 v20, v20, v56
	v_mul_f32_e32 v21, v21, v57
	v_mul_f32_e32 v22, v22, v58
	v_mul_f32_e32 v23, v23, v59
	s_waitcnt lgkmcnt(1)
	v_mul_f32_e32 v40, v40, v60
	v_mul_f32_e32 v41, v41, v61
	v_mul_f32_e32 v42, v42, v62
	v_mul_f32_e32 v43, v43, v63
	v_mul_f32_e32 v24, v24, v60
	v_mul_f32_e32 v25, v25, v61
	v_mul_f32_e32 v26, v26, v62
	v_mul_f32_e32 v27, v27, v63
	s_waitcnt lgkmcnt(0)
	v_mul_f32_e32 v44, v44, v48
	v_mul_f32_e32 v45, v45, v49
	v_mul_f32_e32 v46, v46, v50
	v_mul_f32_e32 v47, v47, v51
	v_mul_f32_e32 v28, v28, v48
	v_mul_f32_e32 v29, v29, v49
	v_mul_f32_e32 v30, v30, v50
	v_mul_f32_e32 v31, v31, v51
	ds_write_b32 v215, v32
	ds_write_b32 v178, v33
	ds_write_b32 v178, v34 offset:272
	ds_write_b32 v178, v35 offset:544
	ds_write_b32 v178, v36 offset:1904
	ds_write_b32 v178, v37 offset:2176
	ds_write_b32 v178, v38 offset:2448
	ds_write_b32 v178, v39 offset:2720
	ds_write_b32 v178, v40 offset:4080
	ds_write_b32 v178, v41 offset:4352
	ds_write_b32 v178, v42 offset:4624
	ds_write_b32 v178, v43 offset:4896
	s_waitcnt lgkmcnt(6)
	ds_write_b32 v178, v44 offset:6256
	ds_write_b32 v178, v45 offset:6528
	ds_write_b32 v178, v46 offset:6800
	ds_write_b32 v178, v47 offset:7072
	ds_write_b32 v215, v16 offset:128
	ds_write_b32 v178, v17 offset:128
	ds_write_b32 v178, v18 offset:400
	ds_write_b32 v178, v19 offset:672
	s_waitcnt lgkmcnt(6)
	ds_write_b32 v178, v20 offset:2032
	ds_write_b32 v178, v21 offset:2304
	ds_write_b32 v178, v22 offset:2576
	ds_write_b32 v178, v23 offset:2848
	ds_write_b32 v178, v24 offset:4208
	ds_write_b32 v178, v25 offset:4480
	ds_write_b32 v178, v26 offset:4752
	ds_write_b32 v178, v27 offset:5024
	s_waitcnt lgkmcnt(6)
	ds_write_b32 v178, v28 offset:6384
	ds_write_b32 v178, v29 offset:6656
	ds_write_b32 v178, v30 offset:6928
	ds_write_b32 v178, v31 offset:7200
	v_cndmask_b32_e64 v24, 0, 1, s[82:83]
	v_cmp_ne_u32_e64 s[8:9], 1, v24
	s_waitcnt lgkmcnt(0)
	ds_read_b128 v[20:23], v179
	ds_read_b128 v[16:19], v179 offset:16
	s_cbranch_vccnz .LBB0_1087
	ds_read_b32 v24, v251
	s_waitcnt vmcnt(3)
	v_lshlrev_b32_e32 v26, 16, v156
	v_and_b32_e32 v27, 0xffff0000, v156
	s_waitcnt lgkmcnt(0)
	v_pk_fma_f32 v[20:21], v[24:25], v[26:27], v[20:21] op_sel_hi:[0,1,1]
	v_lshlrev_b32_e32 v26, 16, v157
	v_and_b32_e32 v27, 0xffff0000, v157
	v_pk_fma_f32 v[22:23], v[24:25], v[26:27], v[22:23] op_sel_hi:[0,1,1]
	v_lshlrev_b32_e32 v26, 16, v158
	v_and_b32_e32 v27, 0xffff0000, v158
	v_pk_fma_f32 v[16:17], v[24:25], v[26:27], v[16:17] op_sel_hi:[0,1,1]
	v_lshlrev_b32_e32 v26, 16, v159
	v_and_b32_e32 v27, 0xffff0000, v159
	v_pk_fma_f32 v[18:19], v[24:25], v[26:27], v[18:19] op_sel_hi:[0,1,1]
